# adds mLSTM pre-pass: all-valid fast path for conv mask application, prefetch waits moved to first consumers (pre-pass A and B)
# baseline (speedup 1.0000x reference)
; #define PB_LOAD(it_, IP, FP) do { const int dir_ = (it_) >= 68, c_ = dir_ ? (it_) - 68 : (it_); const int tk_ = dir_ ? 63 - lane : lane; const int tau_ = c_ * 64 + tk_; \
;             const size_t row_ = tau_ < CTX ? (size_t)(ctxrow0 + tau_) : (size_t)(latrow0 + tau_ - CTX); const float* gs_ = G + row_ * 16 + (dir_ ? 4 : 0) + h; IP = gs_[0]; FP = gs_[8]; } while (0)
; __device__ __forceinline__ void mlstm_unit(const Params& p, int l, int b, int h, LAS unsigned char* lds) {
;     ...
;         float ipn, fpn;
;     ...
;         float ipc, fpc; PB_LOAD(wave, ipc, fpc);
;         for (int it = wave; it < 136; it += 8) {
;             if (it + 8 < 136) PB_LOAD(it + 8, ipn, fpn);
;             const int dir = it >= 68, c = dir ? it - 68 : it; const int tk = dir ? 63 - lane : lane; const int tau = c * 64 + tk;
;             const float ipre = ipc, fpre = fpc;
;             const float lf = fminf(fpre, 0.f) - log1pf(expf(-fabsf(fpre)));
;             float bc = lf;
; #pragma unroll
;             for (int d = 1; d < 64; d <<= 1) { const float y = __shfl_up(bc, d); if (lane >= d) bc += y; }
;             const float av = ipre - bc;
;             float cm = av;
; #pragma unroll
;             for (int d = 1; d < 64; d <<= 1) { const float y = __shfl_up(cm, d); if (lane >= d) cm = fmaxf(cm, y); }
;             SC[(size_t)dir * TK + tau] = (f32x4){bc, av, cm, 0.f};
;             ipc = ipn; fpc = fpn;
;         }
.LBB0_452:
	s_waitcnt vmcnt(2)
	v_mul_f32_e64 v15, |v14|, s33
	v_rndne_f32_e32 v16, v15
	v_sub_f32_e32 v17, v15, v16
	v_fma_f32 v15, |v14|, s33, -v15
	s_mov_b32 s17, 0xb2a5705f
	v_fma_f32 v15, |v14|, s17, v15
	v_add_f32_e32 v15, v17, v15
	v_exp_f32_e32 v15, v15
	v_cvt_i32_f32_e32 v16, v16
	s_mov_b32 s17, 0x42ce8ed0
	v_cmp_ngt_f32_e64 vcc, |v14|, s17
	s_mov_b32 s17, 0xc2b17218
	v_ldexp_f32 v15, v15, v16
	v_cndmask_b32_e32 v15, 0, v15, vcc
	v_cmp_nlt_f32_e64 vcc, |v14|, s17
	v_max_f32_e32 v17, v14, v14
	v_min_f32_e32 v28, 0, v17
	v_cndmask_b32_e32 v29, v226, v15, vcc
	v_add_f32_e32 v16, 1.0, v29
	v_add_f32_e32 v14, -1.0, v16
	v_sub_f32_e32 v15, v14, v16
	v_add_f32_e32 v15, 1.0, v15
	v_sub_f32_e32 v14, v29, v14
	v_add_f32_e32 v17, v14, v15
	v_frexp_mant_f32_e32 v18, v16
	v_cvt_f64_f32_e32 v[14:15], v16
	s_mov_b32 s17, 0x3f2aaaab
	v_frexp_exp_i32_f64_e32 v14, v[14:15]
	v_cmp_gt_f32_e32 vcc, s17, v18
	s_mov_b32 s17, 0x3f317218
	s_cmpk_gt_i32 s24, 0x43
	v_subbrev_co_u32_e32 v22, vcc, 0, v14, vcc
	v_sub_u32_e32 v14, 0, v22
	v_ldexp_f32 v15, v16, v14
	v_add_f32_e32 v16, -1.0, v15
	v_add_f32_e32 v18, 1.0, v15
	v_ldexp_f32 v14, v17, v14
	v_add_f32_e32 v17, 1.0, v16
	v_add_f32_e32 v19, -1.0, v18
	v_sub_f32_e32 v17, v15, v17
	v_sub_f32_e32 v15, v15, v19
	v_add_f32_e32 v17, v14, v17
	v_add_f32_e32 v14, v14, v15
	v_add_f32_e32 v23, v18, v14
	v_rcp_f32_e32 v25, v23
	v_sub_f32_e32 v15, v18, v23
	v_add_f32_e32 v24, v14, v15
	v_add_f32_e32 v15, v16, v17
	v_mul_f32_e32 v27, v15, v25
	v_sub_f32_e32 v14, v16, v15
	v_mul_f32_e32 v16, v23, v27
	v_fma_f32 v18, v27, v23, -v16
	v_fmac_f32_e32 v18, v27, v24
	v_add_f32_e32 v26, v17, v14
	v_add_f32_e32 v14, v16, v18
	v_sub_f32_e32 v17, v15, v14
	v_pk_add_f32 v[20:21], v[14:15], v[16:17] neg_lo:[0,1] neg_hi:[0,1]
	v_mov_b32_e32 v19, v14
	v_pk_add_f32 v[14:15], v[20:21], v[18:19] neg_lo:[0,1] neg_hi:[0,1]
	s_mov_b32 s24, s23
	v_add_f32_e32 v15, v26, v15
	v_add_f32_e32 v14, v14, v15
	v_add_f32_e32 v15, v17, v14
	v_mul_f32_e32 v26, v25, v15
	v_mul_f32_e32 v16, v23, v26
	v_fma_f32 v18, v26, v23, -v16
	v_fmac_f32_e32 v18, v26, v24
	v_sub_f32_e32 v17, v17, v15
	v_add_f32_e32 v23, v14, v17
	v_add_f32_e32 v14, v16, v18
	v_sub_f32_e32 v17, v15, v14
	v_pk_add_f32 v[20:21], v[14:15], v[16:17] neg_lo:[0,1] neg_hi:[0,1]
	v_mov_b32_e32 v19, v14
	v_pk_add_f32 v[14:15], v[20:21], v[18:19] neg_lo:[0,1] neg_hi:[0,1]
	s_nop 0
	v_add_f32_e32 v15, v23, v15
	v_add_f32_e32 v14, v14, v15
	v_add_f32_e32 v15, v27, v26
	v_add_f32_e32 v14, v17, v14
	v_sub_f32_e32 v16, v15, v27
	v_mul_f32_e32 v14, v25, v14
	v_sub_f32_e32 v16, v26, v16
	v_add_f32_e32 v16, v16, v14
	v_add_f32_e32 v18, v15, v16
	v_mul_f32_e32 v19, v18, v18
	v_fmamk_f32 v14, v19, 0x3e9b6dac, v221
	v_fmaak_f32 v195, v19, v14, 0x3f2aaada
	v_cvt_f32_i32_e32 v14, v22
	v_sub_f32_e32 v15, v18, v15
	v_sub_f32_e32 v15, v16, v15
	v_ldexp_f32 v20, v15, 1
	v_mul_f32_e32 v15, v18, v19
	v_ldexp_f32 v17, v18, 1
	v_pk_mul_f32 v[18:19], v[14:15], v[194:195]
	s_nop 0
	v_fma_f32 v16, v14, s17, -v18
	v_fmac_f32_e32 v16, 0xb102e308, v14
	v_pk_add_f32 v[14:15], v[18:19], v[16:17]
	s_mov_b32 s17, 0x7f800000
	v_sub_f32_e32 v17, v15, v17
	v_sub_f32_e32 v17, v19, v17
	v_add_f32_e32 v21, v20, v17
	v_mov_b32_e32 v20, v18
	v_pk_add_f32 v[18:19], v[14:15], v[18:19] neg_lo:[0,1] neg_hi:[0,1]
	v_pk_add_f32 v[22:23], v[14:15], v[20:21]
	v_mov_b32_e32 v17, v14
	v_mov_b32_e32 v19, v23
	v_pk_add_f32 v[24:25], v[16:17], v[18:19] neg_lo:[0,1] neg_hi:[0,1]
	v_pk_add_f32 v[16:17], v[16:17], v[18:19]
	v_mov_b32_e32 v20, v21
	v_pk_add_f32 v[18:19], v[16:17], v[14:15] op_sel:[1,0] op_sel_hi:[0,1] neg_lo:[0,1] neg_hi:[0,1]
	v_pk_add_f32 v[26:27], v[22:23], v[18:19] op_sel_hi:[1,0] neg_lo:[0,1] neg_hi:[0,1]
	v_mov_b32_e32 v22, v23
	v_mov_b32_e32 v23, v17
	v_pk_mov_b32 v[18:19], v[14:15], v[18:19] op_sel:[1,0]
	v_mov_b32_e32 v21, v14
	v_pk_add_f32 v[18:19], v[22:23], v[18:19] neg_lo:[0,1] neg_hi:[0,1]
	v_mov_b32_e32 v26, v24
	v_pk_add_f32 v[14:15], v[20:21], v[18:19] neg_lo:[0,1] neg_hi:[0,1]
	v_mov_b32_e32 v25, v17
	v_pk_add_f32 v[18:19], v[26:27], v[14:15]
	v_cmp_neq_f32_e32 vcc, s17, v29
	v_pk_add_f32 v[20:21], v[18:19], v[18:19] op_sel:[0,1] op_sel_hi:[1,0]
	s_mov_b32 s17, 0x33800000
	v_pk_add_f32 v[16:17], v[16:17], v[20:21] op_sel:[1,0] op_sel_hi:[0,1]
	v_mov_b32_e32 v19, v16
	v_pk_add_f32 v[22:23], v[18:19], v[24:25] neg_lo:[0,1] neg_hi:[0,1]
	v_mov_b32_e32 v15, v20
	v_sub_f32_e32 v17, v18, v22
	v_pk_add_f32 v[14:15], v[14:15], v[22:23] neg_lo:[0,1] neg_hi:[0,1]
	v_sub_f32_e32 v17, v24, v17
	v_add_f32_e32 v14, v14, v17
	v_add_f32_e32 v14, v14, v15
	v_add_f32_e32 v14, v16, v14
	v_cndmask_b32_e32 v14, v226, v14, vcc
	v_cmp_lt_f32_e64 vcc, |v29|, s17
	s_nop 1
	v_cndmask_b32_e32 v14, v14, v29, vcc
	v_sub_f32_e32 v14, v28, v14
	ds_bpermute_b32 v15, v1, v14
	s_cselect_b64 vcc, -1, 0
	s_and_b64 s[28:29], vcc, exec
	s_cselect_b32 s17, 0x11000, 0
	s_add_u32 s28, s20, s17
	s_waitcnt lgkmcnt(0)
	v_add_f32_e32 v15, v14, v15
	v_cndmask_b32_e64 v14, v15, v14, s[4:5]
	ds_bpermute_b32 v15, v2, v14
	s_addc_u32 s29, s21, 0
	s_waitcnt lgkmcnt(0)
	v_add_f32_e32 v15, v14, v15
	v_cndmask_b32_e64 v14, v15, v14, s[6:7]
	ds_bpermute_b32 v15, v3, v14
	s_waitcnt lgkmcnt(0)
	v_add_f32_e32 v15, v14, v15
	v_cndmask_b32_e64 v14, v15, v14, s[8:9]
	ds_bpermute_b32 v15, v4, v14
	s_waitcnt lgkmcnt(0)
	v_add_f32_e32 v15, v14, v15
	v_cndmask_b32_e64 v14, v15, v14, s[10:11]
	ds_bpermute_b32 v15, v5, v14
	s_waitcnt lgkmcnt(0)
	v_add_f32_e32 v15, v14, v15
	v_cndmask_b32_e64 v14, v15, v14, s[12:13]
	ds_bpermute_b32 v15, v6, v14
	s_waitcnt lgkmcnt(0)
	v_add_f32_e32 v15, v14, v15
	v_cndmask_b32_e64 v158, v15, v14, s[0:1]
	s_waitcnt vmcnt(2)
	v_sub_f32_e32 v159, v9, v158
	ds_bpermute_b32 v9, v1, v159
	s_waitcnt lgkmcnt(0)
	v_max_f32_e32 v9, v9, v9
	v_max_f32_e32 v9, v159, v9
	v_cndmask_b32_e64 v9, v9, v159, s[4:5]
	ds_bpermute_b32 v14, v2, v9
	s_waitcnt lgkmcnt(0)
	v_max_f32_e32 v14, v14, v14
	v_max_f32_e32 v14, v9, v14
	v_cndmask_b32_e64 v9, v14, v9, s[6:7]
	ds_bpermute_b32 v14, v3, v9
	s_waitcnt lgkmcnt(0)
	v_max_f32_e32 v14, v14, v14
	v_max_f32_e32 v14, v9, v14
	v_cndmask_b32_e64 v9, v14, v9, s[8:9]
	ds_bpermute_b32 v14, v4, v9
	s_waitcnt lgkmcnt(0)
	v_max_f32_e32 v14, v14, v14
	v_max_f32_e32 v14, v9, v14
	v_cndmask_b32_e64 v9, v14, v9, s[10:11]
	ds_bpermute_b32 v14, v5, v9
	s_waitcnt lgkmcnt(0)
	v_max_f32_e32 v14, v14, v14
	v_max_f32_e32 v14, v9, v14
	v_cndmask_b32_e64 v9, v14, v9, s[12:13]
	ds_bpermute_b32 v14, v6, v9
	v_max_f32_e32 v15, v9, v9
	s_waitcnt lgkmcnt(0)
	v_max_f32_e32 v14, v14, v14
	v_max_f32_e32 v14, v15, v14
	v_cndmask_b32_e64 v160, v14, v9, s[0:1]
	v_cndmask_b32_e32 v14, v8, v7, vcc
	v_ashrrev_i32_e32 v15, 31, v14
	v_lshl_add_u64 v[14:15], v[14:15], 4, s[28:29]
	global_store_dwordx4 v[14:15], v[158:161], off
	v_add_u32_e32 v7, 0x200, v7
	v_add_u32_e32 v8, 0x200, v8
	s_and_b64 vcc, exec, s[18:19]
	s_waitcnt vmcnt(1)
	v_mov_b32_e32 v9, v12
	v_mov_b32_e32 v14, v13
	s_cbranch_vccnz .LBB0_455
